# mixers queue: second item per workgroup assigned statically (no atomic fetch between attention and the first rglru/pool-sample item)
# baseline (speedup 1.0000x reference)
.LBB0_543:
	s_or_b64 exec, exec, s[12:13]
	s_waitcnt vmcnt(0)
	v_readfirstlane_b32 s4, v1
	s_add_i32 s4, s3, s4
	s_add_i32 s4, s3, s4
	v_mov_b32_e32 v1, s53
	v_add_u32_e32 v0, s4, v0
	ds_write_b32 v1, v0

.Lq_remap:
	s_cmpk_lt_i32 s81, 0x104
	s_cselect_b32 s4, 0x182, -4
	s_cmpk_lt_i32 s81, 0x286
	s_cselect_b32 s4, s4, 0
	s_add_i32 s81, s81, s4

.LBB0_577:
	v_sub_f32_e32 v1, v37, v0
	v_exp_f32_e32 v1, v1
	v_sub_f32_e32 v3, v45, v0
	v_exp_f32_e32 v3, v3
	s_waitcnt vmcnt(12)
	v_sub_f32_e32 v4, v47, v0
	v_exp_f32_e32 v4, v4
	v_sub_f32_e32 v5, v46, v0
	v_exp_f32_e32 v5, v5
	v_sub_f32_e32 v6, v8, v0
	v_add_f32_e32 v2, v1, v39
	v_exp_f32_e32 v6, v6
	v_sub_f32_e32 v7, v9, v0
	v_add_f32_e32 v2, v3, v2
	v_exp_f32_e32 v7, v7
	v_sub_f32_e32 v8, v10, v0
	v_add_f32_e32 v2, v4, v2
	v_exp_f32_e32 v8, v8
	v_sub_f32_e32 v9, v11, v0
	v_add_f32_e32 v2, v5, v2
	v_exp_f32_e32 v9, v9
	v_sub_f32_e32 v10, v12, v0
	v_add_f32_e32 v2, v6, v2
	v_exp_f32_e32 v10, v10
	v_sub_f32_e32 v11, v13, v0
	v_add_f32_e32 v2, v7, v2
	v_exp_f32_e32 v11, v11
	v_sub_f32_e32 v12, v14, v0
	v_add_f32_e32 v2, v8, v2
	v_exp_f32_e32 v36, v12
	v_sub_f32_e32 v12, v15, v0
	v_add_f32_e32 v2, v9, v2
	v_exp_f32_e32 v15, v12
	v_sub_f32_e32 v12, v16, v0
	v_add_f32_e32 v2, v10, v2
	v_exp_f32_e32 v37, v12
	v_sub_f32_e32 v12, v17, v0
	v_add_f32_e32 v2, v11, v2
	v_exp_f32_e32 v38, v12
	v_sub_f32_e32 v12, v18, v0
	v_add_f32_e32 v2, v36, v2
	v_exp_f32_e32 v39, v12
	v_sub_f32_e32 v12, v19, v0
	v_add_f32_e32 v2, v15, v2
	v_exp_f32_e32 v45, v12
	v_sub_f32_e32 v12, v20, v0
	v_add_f32_e32 v2, v37, v2
	v_exp_f32_e32 v20, v12
	v_sub_f32_e32 v12, v21, v0
	v_add_f32_e32 v2, v38, v2
	v_exp_f32_e32 v21, v12
	v_sub_f32_e32 v12, v22, v0
	v_add_f32_e32 v2, v39, v2
	v_exp_f32_e32 v22, v12
	v_sub_f32_e32 v12, v23, v0
	v_add_f32_e32 v2, v45, v2
	v_exp_f32_e32 v23, v12
	v_sub_f32_e32 v12, v24, v0
	v_add_f32_e32 v2, v20, v2
	v_exp_f32_e32 v24, v12
	v_sub_f32_e32 v12, v25, v0
	v_add_f32_e32 v2, v21, v2
	v_exp_f32_e32 v25, v12
	v_sub_f32_e32 v12, v26, v0
	v_add_f32_e32 v2, v22, v2
	v_exp_f32_e32 v26, v12
	v_sub_f32_e32 v12, v27, v0
	v_add_f32_e32 v2, v23, v2
	v_exp_f32_e32 v27, v12
	v_sub_f32_e32 v12, v28, v0
	v_add_f32_e32 v2, v24, v2
	v_exp_f32_e32 v28, v12
	v_sub_f32_e32 v12, v29, v0
	v_add_f32_e32 v2, v25, v2
	v_exp_f32_e32 v29, v12
	v_sub_f32_e32 v12, v30, v0
	v_add_f32_e32 v2, v26, v2
	v_exp_f32_e32 v30, v12
	v_sub_f32_e32 v12, v31, v0
	v_add_f32_e32 v2, v27, v2
	v_exp_f32_e32 v31, v12
	v_sub_f32_e32 v12, v32, v0
	v_add_f32_e32 v2, v28, v2
	v_exp_f32_e32 v32, v12
	v_sub_f32_e32 v12, v33, v0
	v_add_f32_e32 v2, v29, v2
	v_exp_f32_e32 v33, v12
	v_sub_f32_e32 v12, v34, v0
	v_add_f32_e32 v2, v30, v2
	v_exp_f32_e32 v34, v12
	v_sub_f32_e32 v12, v35, v0
	v_add_f32_e32 v2, v31, v2
	v_exp_f32_e32 v35, v12
	v_sub_f32_e32 v12, v41, v0
	v_add_f32_e32 v2, v32, v2
	v_exp_f32_e32 v41, v12
	v_sub_f32_e32 v12, v40, v0
	v_add_f32_e32 v2, v33, v2
	v_exp_f32_e32 v40, v12
	v_sub_f32_e32 v12, v43, v0
	v_add_f32_e32 v2, v34, v2
	v_exp_f32_e32 v43, v12
	v_sub_f32_e32 v12, v42, v0
	v_add_f32_e32 v2, v35, v2
	v_exp_f32_e32 v42, v12
	v_add_f32_e32 v2, v41, v2
	v_add_f32_e32 v2, v40, v2
	v_add_f32_e32 v2, v43, v2
	v_add_f32_e32 v2, v42, v2
	ds_bpermute_b32 v12, v69, v2
	v_sub_f32_e32 v0, v67, v0
	v_exp_f32_e32 v0, v0
	v_cvt_pk_bf16_f32 v16, v44, v44
	v_cvt_pk_bf16_f32 v17, v44, v44
	s_waitcnt lgkmcnt(0)
	v_add_f32_e32 v2, v2, v12
	ds_bpermute_b32 v12, v71, v2
	v_cvt_pk_bf16_f32 v18, v1, v3
	v_cvt_pk_bf16_f32 v19, v4, v5
	v_mov_b32_e32 v61, v63
	s_waitcnt lgkmcnt(0)
	v_add_f32_e32 v2, v2, v12
	v_add_f32_e32 v46, v0, v2
	v_cvt_pk_bf16_f32 v12, v6, v7
	v_cvt_pk_bf16_f32 v13, v8, v9
	v_cvt_pk_bf16_f32 v14, v10, v11
	v_cvt_pk_bf16_f32 v15, v36, v15
	v_cvt_pk_bf16_f32 v8, v37, v38
	v_cvt_pk_bf16_f32 v9, v39, v45
	v_cvt_pk_bf16_f32 v10, v20, v21
	v_div_scale_f32 v20, s[10:11], v46, v46, 1.0
	v_rcp_f32_e32 v21, v20
	v_cvt_pk_bf16_f32 v11, v22, v23
	v_cvt_pk_bf16_f32 v4, v24, v25
	v_cvt_pk_bf16_f32 v5, v26, v27
	v_cvt_pk_bf16_f32 v6, v28, v29
	v_cvt_pk_bf16_f32 v7, v30, v31
	s_nop 0
	v_fma_f32 v22, -v20, v21, 1.0
	v_fmac_f32_e32 v21, v22, v21
	v_div_scale_f32 v22, vcc, 1.0, v46, 1.0
	v_mul_f32_e32 v23, v22, v21
	v_fma_f32 v24, -v20, v23, v22
	v_cvt_pk_bf16_f32 v0, v32, v33
	v_cvt_pk_bf16_f32 v1, v34, v35
	v_cvt_pk_bf16_f32 v2, v41, v40
	v_cvt_pk_bf16_f32 v3, v43, v42
	v_fmac_f32_e32 v23, v24, v21
	ds_read2_b64 v[24:27], v55 offset0:8 offset1:12
	ds_read2_b64 v[28:31], v55 offset0:16 offset1:20
	s_waitcnt lgkmcnt(1)
	v_mfma_f32_16x16x32_bf16 v[24:27], v[24:27], v[16:19], 0
	v_fma_f32 v20, -v20, v23, v22
	v_div_fmas_f32 v20, v20, v21, v23
	v_div_fixup_f32 v22, v20, v46, 1.0
	s_waitcnt lgkmcnt(0)
	v_mfma_f32_16x16x32_bf16 v[24:27], v[28:31], v[12:15], v[24:27]
	ds_read2_b64 v[28:31], v55 offset0:24 offset1:28
	v_lshlrev_b64 v[20:21], 11, v[60:61]
	v_lshl_add_u64 v[20:21], v[52:53], 0, v[20:21]
	s_waitcnt lgkmcnt(0)
	v_mfma_f32_16x16x32_bf16 v[24:27], v[28:31], v[8:11], v[24:27]
	ds_read2_b64 v[28:31], v55 offset0:32 offset1:36
	s_waitcnt lgkmcnt(0)
	v_mfma_f32_16x16x32_bf16 v[24:27], v[28:31], v[4:7], v[24:27]
	ds_read2_b64 v[28:31], v55 offset0:40 offset1:44
	s_waitcnt lgkmcnt(0)
	v_mfma_f32_16x16x32_bf16 v[24:27], v[28:31], v[0:3], v[24:27]
	s_nop 7
	v_pk_mul_f32 v[24:25], v[24:25], v[22:23] op_sel_hi:[1,0]
	v_pk_mul_f32 v[26:27], v[26:27], v[22:23] op_sel_hi:[1,0]
	v_cvt_pk_bf16_f32 v24, v24, v25
	s_nop 0
	v_cvt_pk_bf16_f32 v25, v26, v27
	global_store_dwordx2 v[20:21], v[24:25], off
	ds_read2_b64 v[24:27], v56 offset0:40 offset1:44
	ds_read2_b64 v[28:31], v56 offset0:48 offset1:52
	s_waitcnt lgkmcnt(1)
	v_mfma_f32_16x16x32_bf16 v[24:27], v[24:27], v[16:19], 0
	s_waitcnt lgkmcnt(0)
	v_mfma_f32_16x16x32_bf16 v[24:27], v[28:31], v[12:15], v[24:27]
	ds_read2_b64 v[28:31], v56 offset0:56 offset1:60
	s_waitcnt lgkmcnt(0)
	v_mfma_f32_16x16x32_bf16 v[24:27], v[28:31], v[8:11], v[24:27]
	ds_read2_b64 v[28:31], v56 offset0:64 offset1:68
	s_waitcnt lgkmcnt(0)
	v_mfma_f32_16x16x32_bf16 v[24:27], v[28:31], v[4:7], v[24:27]
	ds_read2_b64 v[28:31], v56 offset0:72 offset1:76
	s_waitcnt lgkmcnt(0)
	v_mfma_f32_16x16x32_bf16 v[24:27], v[28:31], v[0:3], v[24:27]
	s_nop 7
	v_pk_mul_f32 v[24:25], v[22:23], v[24:25] op_sel_hi:[0,1]
	v_pk_mul_f32 v[26:27], v[22:23], v[26:27] op_sel_hi:[0,1]
	v_cvt_pk_bf16_f32 v24, v24, v25
	v_cvt_pk_bf16_f32 v25, v26, v27
	global_store_dwordx2 v[20:21], v[24:25], off offset:32
	ds_read2_b64 v[24:27], v57 offset0:72 offset1:76
	ds_read2_b64 v[28:31], v57 offset0:80 offset1:84
	s_waitcnt lgkmcnt(1)
	v_mfma_f32_16x16x32_bf16 v[24:27], v[24:27], v[16:19], 0
	s_waitcnt lgkmcnt(0)
	v_mfma_f32_16x16x32_bf16 v[24:27], v[28:31], v[12:15], v[24:27]
	ds_read2_b64 v[28:31], v57 offset0:88 offset1:92
	s_waitcnt lgkmcnt(0)
	v_mfma_f32_16x16x32_bf16 v[24:27], v[28:31], v[8:11], v[24:27]
	ds_read2_b64 v[28:31], v57 offset0:96 offset1:100
	s_waitcnt lgkmcnt(0)
	v_mfma_f32_16x16x32_bf16 v[24:27], v[28:31], v[4:7], v[24:27]
	ds_read2_b64 v[28:31], v57 offset0:104 offset1:108
	s_waitcnt lgkmcnt(0)
	v_mfma_f32_16x16x32_bf16 v[24:27], v[28:31], v[0:3], v[24:27]
	s_nop 7
	v_pk_mul_f32 v[24:25], v[22:23], v[24:25] op_sel_hi:[0,1]
	v_pk_mul_f32 v[26:27], v[22:23], v[26:27] op_sel_hi:[0,1]
	v_cvt_pk_bf16_f32 v24, v24, v25
	v_cvt_pk_bf16_f32 v25, v26, v27
	global_store_dwordx2 v[20:21], v[24:25], off offset:64
	ds_read2_b64 v[24:27], v58 offset0:104 offset1:108
	s_waitcnt lgkmcnt(0)
	v_mfma_f32_16x16x32_bf16 v[16:19], v[24:27], v[16:19], 0
	ds_read2_b64 v[24:27], v58 offset0:112 offset1:116
	s_waitcnt lgkmcnt(0)
	v_mfma_f32_16x16x32_bf16 v[12:15], v[24:27], v[12:15], v[16:19]
	s_nop 4
	ds_read2_b64 v[16:19], v58 offset0:120 offset1:124
	s_waitcnt lgkmcnt(0)
	v_mfma_f32_16x16x32_bf16 v[8:11], v[16:19], v[8:11], v[12:15]
	s_nop 2
	ds_read2_b64 v[12:15], v58 offset0:128 offset1:132
	s_waitcnt lgkmcnt(0)
	v_mfma_f32_16x16x32_bf16 v[4:7], v[12:15], v[4:7], v[8:11]
	s_nop 2
	ds_read2_b64 v[8:11], v58 offset0:136 offset1:140
	s_waitcnt lgkmcnt(0)
	v_mfma_f32_16x16x32_bf16 v[0:3], v[8:11], v[0:3], v[4:7]
	s_nop 7
	v_pk_mul_f32 v[0:1], v[22:23], v[0:1] op_sel_hi:[0,1]
	v_pk_mul_f32 v[2:3], v[22:23], v[2:3] op_sel_hi:[0,1]
	v_cvt_pk_bf16_f32 v0, v0, v1
	v_cvt_pk_bf16_f32 v1, v2, v3
	global_store_dwordx2 v[20:21], v[0:1], off offset:96
	s_barrier
	s_addk_i32 s81, 0x100
	s_branch .Lq_remap
